# code placement: the four GEMM K-loop heads aligned to 64 bytes (.p2align 6)
# speedup vs baseline: 1.0028x; 1.0027x over previous
.LBB0_369:
	s_and_b64 s[38:39], s[0:1], exec
	s_cselect_b32 s19, s53, s11
	s_cselect_b32 s40, s52, s10
	s_cselect_b32 s41, s37, s17
	s_cselect_b32 s54, s36, s16
	s_add_u32 s38, s10, 0x40080
	s_addc_u32 s39, s11, 0
	s_add_u32 s55, s16, 0x100
	v_mov_b32_e32 v0, 0
	s_mov_b32 s6, s97
	s_addc_u32 s70, s17, 0
	s_mov_b32 s71, -2
	v_mov_b32_e32 v1, v0
	v_mov_b32_e32 v2, v0
	v_mov_b32_e32 v3, v0
	v_mov_b32_e32 v4, v0
	v_mov_b32_e32 v5, v0
	v_mov_b32_e32 v6, v0
	v_mov_b32_e32 v7, v0
	v_mov_b32_e32 v16, v0
	v_mov_b32_e32 v17, v0
	v_mov_b32_e32 v18, v0
	v_mov_b32_e32 v19, v0
	v_mov_b32_e32 v20, v0
	v_mov_b32_e32 v21, v0
	v_mov_b32_e32 v22, v0
	v_mov_b32_e32 v23, v0
	v_mov_b32_e32 v32, v0
	v_mov_b32_e32 v33, v0
	v_mov_b32_e32 v34, v0
	v_mov_b32_e32 v35, v0
	v_mov_b32_e32 v36, v0
	v_mov_b32_e32 v37, v0
	v_mov_b32_e32 v38, v0
	v_mov_b32_e32 v39, v0
	v_mov_b32_e32 v48, v0
	v_mov_b32_e32 v49, v0
	v_mov_b32_e32 v50, v0
	v_mov_b32_e32 v51, v0
	v_mov_b32_e32 v52, v0
	v_mov_b32_e32 v53, v0
	v_mov_b32_e32 v54, v0
	v_mov_b32_e32 v55, v0
	v_mov_b32_e32 v8, v0
	v_mov_b32_e32 v9, v0
	v_mov_b32_e32 v10, v0
	v_mov_b32_e32 v11, v0
	v_mov_b32_e32 v12, v0
	v_mov_b32_e32 v13, v0
	v_mov_b32_e32 v14, v0
	v_mov_b32_e32 v15, v0
	v_mov_b32_e32 v24, v0
	v_mov_b32_e32 v25, v0
	v_mov_b32_e32 v26, v0
	v_mov_b32_e32 v27, v0
	v_mov_b32_e32 v28, v0
	v_mov_b32_e32 v29, v0
	v_mov_b32_e32 v30, v0
	v_mov_b32_e32 v31, v0
	v_mov_b32_e32 v40, v0
	v_mov_b32_e32 v41, v0
	v_mov_b32_e32 v42, v0
	v_mov_b32_e32 v43, v0
	v_mov_b32_e32 v44, v0
	v_mov_b32_e32 v45, v0
	v_mov_b32_e32 v46, v0
	v_mov_b32_e32 v47, v0
	v_mov_b32_e32 v56, v0
	v_mov_b32_e32 v57, v0
	v_mov_b32_e32 v58, v0
	v_mov_b32_e32 v59, v0
	v_mov_b32_e32 v60, v0
	v_mov_b32_e32 v61, v0
	v_mov_b32_e32 v62, v0
	v_mov_b32_e32 v63, v0
	v_mov_b32_e32 v64, v0
	v_mov_b32_e32 v65, v0
	v_mov_b32_e32 v66, v0
	v_mov_b32_e32 v67, v0
	v_mov_b32_e32 v68, v0
	v_mov_b32_e32 v69, v0
	v_mov_b32_e32 v70, v0
	v_mov_b32_e32 v71, v0
	v_mov_b32_e32 v80, v0
	v_mov_b32_e32 v81, v0
	v_mov_b32_e32 v82, v0
	v_mov_b32_e32 v83, v0
	v_mov_b32_e32 v84, v0
	v_mov_b32_e32 v85, v0
	v_mov_b32_e32 v86, v0
	v_mov_b32_e32 v87, v0
	v_mov_b32_e32 v96, v0
	v_mov_b32_e32 v97, v0
	v_mov_b32_e32 v98, v0
	v_mov_b32_e32 v99, v0
	v_mov_b32_e32 v100, v0
	v_mov_b32_e32 v101, v0
	v_mov_b32_e32 v102, v0
	v_mov_b32_e32 v103, v0
	v_mov_b32_e32 v112, v0
	v_mov_b32_e32 v113, v0
	v_mov_b32_e32 v114, v0
	v_mov_b32_e32 v115, v0
	v_mov_b32_e32 v116, v0
	v_mov_b32_e32 v117, v0
	v_mov_b32_e32 v118, v0
	v_mov_b32_e32 v119, v0
	v_mov_b32_e32 v72, v0
	v_mov_b32_e32 v73, v0
	v_mov_b32_e32 v74, v0
	v_mov_b32_e32 v75, v0
	v_mov_b32_e32 v76, v0
	v_mov_b32_e32 v77, v0
	v_mov_b32_e32 v78, v0
	v_mov_b32_e32 v79, v0
	v_mov_b32_e32 v88, v0
	v_mov_b32_e32 v89, v0
	v_mov_b32_e32 v90, v0
	v_mov_b32_e32 v91, v0
	v_mov_b32_e32 v92, v0
	v_mov_b32_e32 v93, v0
	v_mov_b32_e32 v94, v0
	v_mov_b32_e32 v95, v0
	v_mov_b32_e32 v104, v0
	v_mov_b32_e32 v105, v0
	v_mov_b32_e32 v106, v0
	v_mov_b32_e32 v107, v0
	v_mov_b32_e32 v108, v0
	v_mov_b32_e32 v109, v0
	v_mov_b32_e32 v110, v0
	v_mov_b32_e32 v111, v0
	v_mov_b32_e32 v120, v0
	v_mov_b32_e32 v121, v0
	v_mov_b32_e32 v122, v0
	v_mov_b32_e32 v123, v0
	v_mov_b32_e32 v124, v0
	v_mov_b32_e32 v125, v0
	v_mov_b32_e32 v126, v0
	v_mov_b32_e32 v127, v0
	.p2align	6

.LBB0_556:
	s_add_u32 s52, s10, 0x20080
	s_addc_u32 s53, s11, 0
	s_add_u32 s41, s16, 0x100
	v_mov_b32_e32 v0, 0
	s_addc_u32 s79, s17, 0
	s_mov_b32 s80, -2
	v_mov_b32_e32 v1, v0
	v_mov_b32_e32 v2, v0
	v_mov_b32_e32 v3, v0
	v_mov_b32_e32 v4, v0
	v_mov_b32_e32 v5, v0
	v_mov_b32_e32 v6, v0
	v_mov_b32_e32 v7, v0
	v_mov_b32_e32 v8, v0
	v_mov_b32_e32 v9, v0
	v_mov_b32_e32 v10, v0
	v_mov_b32_e32 v11, v0
	v_mov_b32_e32 v12, v0
	v_mov_b32_e32 v13, v0
	v_mov_b32_e32 v14, v0
	v_mov_b32_e32 v15, v0
	v_mov_b32_e32 v24, v0
	v_mov_b32_e32 v25, v0
	v_mov_b32_e32 v26, v0
	v_mov_b32_e32 v27, v0
	v_mov_b32_e32 v28, v0
	v_mov_b32_e32 v29, v0
	v_mov_b32_e32 v30, v0
	v_mov_b32_e32 v31, v0
	v_mov_b32_e32 v40, v0
	v_mov_b32_e32 v41, v0
	v_mov_b32_e32 v42, v0
	v_mov_b32_e32 v43, v0
	v_mov_b32_e32 v44, v0
	v_mov_b32_e32 v45, v0
	v_mov_b32_e32 v46, v0
	v_mov_b32_e32 v47, v0
	v_mov_b32_e32 v16, v0
	v_mov_b32_e32 v17, v0
	v_mov_b32_e32 v18, v0
	v_mov_b32_e32 v19, v0
	v_mov_b32_e32 v20, v0
	v_mov_b32_e32 v21, v0
	v_mov_b32_e32 v22, v0
	v_mov_b32_e32 v23, v0
	v_mov_b32_e32 v32, v0
	v_mov_b32_e32 v33, v0
	v_mov_b32_e32 v34, v0
	v_mov_b32_e32 v35, v0
	v_mov_b32_e32 v36, v0
	v_mov_b32_e32 v37, v0
	v_mov_b32_e32 v38, v0
	v_mov_b32_e32 v39, v0
	v_mov_b32_e32 v48, v0
	v_mov_b32_e32 v49, v0
	v_mov_b32_e32 v50, v0
	v_mov_b32_e32 v51, v0
	v_mov_b32_e32 v52, v0
	v_mov_b32_e32 v53, v0
	v_mov_b32_e32 v54, v0
	v_mov_b32_e32 v55, v0
	v_mov_b32_e32 v56, v0
	v_mov_b32_e32 v57, v0
	v_mov_b32_e32 v58, v0
	v_mov_b32_e32 v59, v0
	v_mov_b32_e32 v60, v0
	v_mov_b32_e32 v61, v0
	v_mov_b32_e32 v62, v0
	v_mov_b32_e32 v63, v0
	v_mov_b32_e32 v64, v0
	v_mov_b32_e32 v65, v0
	v_mov_b32_e32 v66, v0
	v_mov_b32_e32 v67, v0
	v_mov_b32_e32 v68, v0
	v_mov_b32_e32 v69, v0
	v_mov_b32_e32 v70, v0
	v_mov_b32_e32 v71, v0
	v_mov_b32_e32 v72, v0
	v_mov_b32_e32 v73, v0
	v_mov_b32_e32 v74, v0
	v_mov_b32_e32 v75, v0
	v_mov_b32_e32 v76, v0
	v_mov_b32_e32 v77, v0
	v_mov_b32_e32 v78, v0
	v_mov_b32_e32 v79, v0
	v_mov_b32_e32 v88, v0
	v_mov_b32_e32 v89, v0
	v_mov_b32_e32 v90, v0
	v_mov_b32_e32 v91, v0
	v_mov_b32_e32 v92, v0
	v_mov_b32_e32 v93, v0
	v_mov_b32_e32 v94, v0
	v_mov_b32_e32 v95, v0
	v_mov_b32_e32 v104, v0
	v_mov_b32_e32 v105, v0
	v_mov_b32_e32 v106, v0
	v_mov_b32_e32 v107, v0
	v_mov_b32_e32 v108, v0
	v_mov_b32_e32 v109, v0
	v_mov_b32_e32 v110, v0
	v_mov_b32_e32 v111, v0
	v_mov_b32_e32 v80, v0
	v_mov_b32_e32 v81, v0
	v_mov_b32_e32 v82, v0
	v_mov_b32_e32 v83, v0
	v_mov_b32_e32 v84, v0
	v_mov_b32_e32 v85, v0
	v_mov_b32_e32 v86, v0
	v_mov_b32_e32 v87, v0
	v_mov_b32_e32 v96, v0
	v_mov_b32_e32 v97, v0
	v_mov_b32_e32 v98, v0
	v_mov_b32_e32 v99, v0
	v_mov_b32_e32 v100, v0
	v_mov_b32_e32 v101, v0
	v_mov_b32_e32 v102, v0
	v_mov_b32_e32 v103, v0
	v_mov_b32_e32 v112, v0
	v_mov_b32_e32 v113, v0
	v_mov_b32_e32 v114, v0
	v_mov_b32_e32 v115, v0
	v_mov_b32_e32 v116, v0
	v_mov_b32_e32 v117, v0
	v_mov_b32_e32 v118, v0
	v_mov_b32_e32 v119, v0
	v_mov_b32_e32 v120, v0
	v_mov_b32_e32 v121, v0
	v_mov_b32_e32 v122, v0
	v_mov_b32_e32 v123, v0
	v_mov_b32_e32 v124, v0
	v_mov_b32_e32 v125, v0
	v_mov_b32_e32 v126, v0
	v_mov_b32_e32 v127, v0
	.p2align	6

.LBB0_1579:
	s_ashr_i32 s53, s52, 31
	s_ashr_i32 s51, s50, 31
	s_lshl_b64 s[56:57], s[52:53], 19
	s_add_u32 s4, s75, s56
	s_addc_u32 s5, s76, s57
	s_lshl_b64 s[58:59], s[50:51], 17
	s_add_u32 s4, s4, s58
	s_addc_u32 s5, s5, s59
	s_add_u32 s16, s46, 0x40080
	s_addc_u32 s17, s47, 0
	s_add_u32 s37, s10, 0x100
	v_mov_b32_e32 v0, 0
	v_lshl_add_u64 v[202:203], s[16:17], 0, v[198:199]
	v_lshl_add_u64 v[204:205], s[16:17], 0, v[200:201]
	s_addc_u32 s51, s11, 0
	s_mov_b64 s[62:63], 0
	s_mov_b32 s53, -2
	v_mov_b32_e32 v1, v0
	v_mov_b32_e32 v2, v0
	v_mov_b32_e32 v3, v0
	v_mov_b32_e32 v4, v0
	v_mov_b32_e32 v5, v0
	v_mov_b32_e32 v6, v0
	v_mov_b32_e32 v7, v0
	v_mov_b32_e32 v12, v0
	v_mov_b32_e32 v13, v0
	v_mov_b32_e32 v14, v0
	v_mov_b32_e32 v15, v0
	v_mov_b32_e32 v20, v0
	v_mov_b32_e32 v21, v0
	v_mov_b32_e32 v22, v0
	v_mov_b32_e32 v23, v0
	v_mov_b32_e32 v28, v0
	v_mov_b32_e32 v29, v0
	v_mov_b32_e32 v30, v0
	v_mov_b32_e32 v31, v0
	v_mov_b32_e32 v36, v0
	v_mov_b32_e32 v37, v0
	v_mov_b32_e32 v38, v0
	v_mov_b32_e32 v39, v0
	v_mov_b32_e32 v44, v0
	v_mov_b32_e32 v45, v0
	v_mov_b32_e32 v46, v0
	v_mov_b32_e32 v47, v0
	v_mov_b32_e32 v52, v0
	v_mov_b32_e32 v53, v0
	v_mov_b32_e32 v54, v0
	v_mov_b32_e32 v55, v0
	v_mov_b32_e32 v8, v0
	v_mov_b32_e32 v9, v0
	v_mov_b32_e32 v10, v0
	v_mov_b32_e32 v11, v0
	v_mov_b32_e32 v16, v0
	v_mov_b32_e32 v17, v0
	v_mov_b32_e32 v18, v0
	v_mov_b32_e32 v19, v0
	v_mov_b32_e32 v24, v0
	v_mov_b32_e32 v25, v0
	v_mov_b32_e32 v26, v0
	v_mov_b32_e32 v27, v0
	v_mov_b32_e32 v32, v0
	v_mov_b32_e32 v33, v0
	v_mov_b32_e32 v34, v0
	v_mov_b32_e32 v35, v0
	v_mov_b32_e32 v40, v0
	v_mov_b32_e32 v41, v0
	v_mov_b32_e32 v42, v0
	v_mov_b32_e32 v43, v0
	v_mov_b32_e32 v48, v0
	v_mov_b32_e32 v49, v0
	v_mov_b32_e32 v50, v0
	v_mov_b32_e32 v51, v0
	v_mov_b32_e32 v56, v0
	v_mov_b32_e32 v57, v0
	v_mov_b32_e32 v58, v0
	v_mov_b32_e32 v59, v0
	v_mov_b32_e32 v60, v0
	v_mov_b32_e32 v61, v0
	v_mov_b32_e32 v62, v0
	v_mov_b32_e32 v63, v0
	v_mov_b32_e32 v64, v0
	v_mov_b32_e32 v65, v0
	v_mov_b32_e32 v66, v0
	v_mov_b32_e32 v67, v0
	v_mov_b32_e32 v68, v0
	v_mov_b32_e32 v69, v0
	v_mov_b32_e32 v70, v0
	v_mov_b32_e32 v71, v0
	v_mov_b32_e32 v76, v0
	v_mov_b32_e32 v77, v0
	v_mov_b32_e32 v78, v0
	v_mov_b32_e32 v79, v0
	v_mov_b32_e32 v84, v0
	v_mov_b32_e32 v85, v0
	v_mov_b32_e32 v86, v0
	v_mov_b32_e32 v87, v0
	v_mov_b32_e32 v92, v0
	v_mov_b32_e32 v93, v0
	v_mov_b32_e32 v94, v0
	v_mov_b32_e32 v95, v0
	v_mov_b32_e32 v100, v0
	v_mov_b32_e32 v101, v0
	v_mov_b32_e32 v102, v0
	v_mov_b32_e32 v103, v0
	v_mov_b32_e32 v112, v0
	v_mov_b32_e32 v113, v0
	v_mov_b32_e32 v114, v0
	v_mov_b32_e32 v115, v0
	v_mov_b32_e32 v116, v0
	v_mov_b32_e32 v117, v0
	v_mov_b32_e32 v118, v0
	v_mov_b32_e32 v119, v0
	v_mov_b32_e32 v72, v0
	v_mov_b32_e32 v73, v0
	v_mov_b32_e32 v74, v0
	v_mov_b32_e32 v75, v0
	v_mov_b32_e32 v80, v0
	v_mov_b32_e32 v81, v0
	v_mov_b32_e32 v82, v0
	v_mov_b32_e32 v83, v0
	v_mov_b32_e32 v88, v0
	v_mov_b32_e32 v89, v0
	v_mov_b32_e32 v90, v0
	v_mov_b32_e32 v91, v0
	v_mov_b32_e32 v96, v0
	v_mov_b32_e32 v97, v0
	v_mov_b32_e32 v98, v0
	v_mov_b32_e32 v99, v0
	v_mov_b32_e32 v104, v0
	v_mov_b32_e32 v105, v0
	v_mov_b32_e32 v106, v0
	v_mov_b32_e32 v107, v0
	v_mov_b32_e32 v108, v0
	v_mov_b32_e32 v109, v0
	v_mov_b32_e32 v110, v0
	v_mov_b32_e32 v111, v0
	v_mov_b32_e32 v120, v0
	v_mov_b32_e32 v121, v0
	v_mov_b32_e32 v122, v0
	v_mov_b32_e32 v123, v0
	v_mov_b32_e32 v124, v0
	v_mov_b32_e32 v125, v0
	v_mov_b32_e32 v126, v0
	v_mov_b32_e32 v127, v0
	s_branch .LBB0_1581
	.p2align	6

.LBB0_1652:
	s_add_u32 s38, s16, 0x40080
	s_addc_u32 s39, s17, 0
	s_add_u32 s42, s10, 0x100
	v_mov_b32_e32 v0, 0
	s_addc_u32 s43, s11, 0
	s_mov_b32 s53, -2
	s_waitcnt lgkmcnt(0)
	v_mov_b32_e32 v1, v0
	v_mov_b32_e32 v2, v0
	v_mov_b32_e32 v3, v0
	v_mov_b32_e32 v4, v0
	v_mov_b32_e32 v5, v0
	v_mov_b32_e32 v6, v0
	v_mov_b32_e32 v7, v0
	v_mov_b32_e32 v16, v0
	v_mov_b32_e32 v17, v0
	v_mov_b32_e32 v18, v0
	v_mov_b32_e32 v19, v0
	v_mov_b32_e32 v20, v0
	v_mov_b32_e32 v21, v0
	v_mov_b32_e32 v22, v0
	v_mov_b32_e32 v23, v0
	v_mov_b32_e32 v32, v0
	v_mov_b32_e32 v33, v0
	v_mov_b32_e32 v34, v0
	v_mov_b32_e32 v35, v0
	v_mov_b32_e32 v36, v0
	v_mov_b32_e32 v37, v0
	v_mov_b32_e32 v38, v0
	v_mov_b32_e32 v39, v0
	v_mov_b32_e32 v48, v0
	v_mov_b32_e32 v49, v0
	v_mov_b32_e32 v50, v0
	v_mov_b32_e32 v51, v0
	v_mov_b32_e32 v52, v0
	v_mov_b32_e32 v53, v0
	v_mov_b32_e32 v54, v0
	v_mov_b32_e32 v55, v0
	v_mov_b32_e32 v8, v0
	v_mov_b32_e32 v9, v0
	v_mov_b32_e32 v10, v0
	v_mov_b32_e32 v11, v0
	v_mov_b32_e32 v12, v0
	v_mov_b32_e32 v13, v0
	v_mov_b32_e32 v14, v0
	v_mov_b32_e32 v15, v0
	v_mov_b32_e32 v24, v0
	v_mov_b32_e32 v25, v0
	v_mov_b32_e32 v26, v0
	v_mov_b32_e32 v27, v0
	v_mov_b32_e32 v28, v0
	v_mov_b32_e32 v29, v0
	v_mov_b32_e32 v30, v0
	v_mov_b32_e32 v31, v0
	v_mov_b32_e32 v40, v0
	v_mov_b32_e32 v41, v0
	v_mov_b32_e32 v42, v0
	v_mov_b32_e32 v43, v0
	v_mov_b32_e32 v44, v0
	v_mov_b32_e32 v45, v0
	v_mov_b32_e32 v46, v0
	v_mov_b32_e32 v47, v0
	v_mov_b32_e32 v56, v0
	v_mov_b32_e32 v57, v0
	v_mov_b32_e32 v58, v0
	v_mov_b32_e32 v59, v0
	v_mov_b32_e32 v64, v0
	v_mov_b32_e32 v65, v0
	v_mov_b32_e32 v66, v0
	v_mov_b32_e32 v67, v0
	v_mov_b32_e32 v80, v0
	v_mov_b32_e32 v81, v0
	v_mov_b32_e32 v82, v0
	v_mov_b32_e32 v83, v0
	v_mov_b32_e32 v84, v0
	v_mov_b32_e32 v85, v0
	v_mov_b32_e32 v86, v0
	v_mov_b32_e32 v87, v0
	v_mov_b32_e32 v96, v0
	v_mov_b32_e32 v97, v0
	v_mov_b32_e32 v98, v0
	v_mov_b32_e32 v99, v0
	v_mov_b32_e32 v100, v0
	v_mov_b32_e32 v101, v0
	v_mov_b32_e32 v102, v0
	v_mov_b32_e32 v103, v0
	v_mov_b32_e32 v112, v0
	v_mov_b32_e32 v113, v0
	v_mov_b32_e32 v114, v0
	v_mov_b32_e32 v115, v0
	v_mov_b32_e32 v116, v0
	v_mov_b32_e32 v117, v0
	v_mov_b32_e32 v118, v0
	v_mov_b32_e32 v119, v0
	v_mov_b32_e32 v128, v0
	v_mov_b32_e32 v129, v0
	v_mov_b32_e32 v130, v0
	v_mov_b32_e32 v131, v0
	v_mov_b32_e32 v132, v0
	v_mov_b32_e32 v133, v0
	v_mov_b32_e32 v134, v0
	v_mov_b32_e32 v135, v0
	v_mov_b32_e32 v88, v0
	v_mov_b32_e32 v89, v0
	v_mov_b32_e32 v90, v0
	v_mov_b32_e32 v91, v0
	v_mov_b32_e32 v92, v0
	v_mov_b32_e32 v93, v0
	v_mov_b32_e32 v94, v0
	v_mov_b32_e32 v95, v0
	v_mov_b32_e32 v104, v0
	v_mov_b32_e32 v105, v0
	v_mov_b32_e32 v106, v0
	v_mov_b32_e32 v107, v0
	v_mov_b32_e32 v108, v0
	v_mov_b32_e32 v109, v0
	v_mov_b32_e32 v110, v0
	v_mov_b32_e32 v111, v0
	v_mov_b32_e32 v120, v0
	v_mov_b32_e32 v121, v0
	v_mov_b32_e32 v122, v0
	v_mov_b32_e32 v123, v0
	v_mov_b32_e32 v124, v0
	v_mov_b32_e32 v125, v0
	v_mov_b32_e32 v126, v0
	v_mov_b32_e32 v127, v0
	v_mov_b32_e32 v136, v0
	v_mov_b32_e32 v137, v0
	v_mov_b32_e32 v138, v0
	v_mov_b32_e32 v139, v0
	v_mov_b32_e32 v140, v0
	v_mov_b32_e32 v141, v0
	v_mov_b32_e32 v142, v0
	v_mov_b32_e32 v143, v0
	.p2align	6
